# seams 2-12: hand-written barrier body, all workgroups poll the cross-XCC arrival counter (no returning top atomic, no release flag hop)
# speedup vs baseline: 1.0289x; 1.0067x over previous
; __device__ __forceinline__ unsigned xb_ld(unsigned* p)              { return __hip_atomic_load(p, __ATOMIC_RELAXED, __HIP_MEMORY_SCOPE_AGENT); }
; __device__ __forceinline__ unsigned xb_add(unsigned* p, unsigned v) { return __hip_atomic_fetch_add(p, v, __ATOMIC_RELAXED, __HIP_MEMORY_SCOPE_AGENT); }
; #define XB_SPIN(cond, bar) do { unsigned _sp = 0; while (cond) { __builtin_amdgcn_s_sleep(1); \
;     if ((++_sp & 255u) == 0u) { if (xb_ld(&(bar)[XB_TMO])) break; if (_sp > XB_SPIN_CAP) { atomicAdd(&(bar)[XB_TMO], 1u); break; } } } } while (0)
; __device__ __forceinline__ void xcd_barrier(const XcdBarrier& b) {
;     asm volatile("s_waitcnt vmcnt(0)" ::: "memory");
;     __syncthreads();
;     if (threadIdx.x == 0) {
;         unsigned* bar = b.bar;
;         __builtin_amdgcn_s_waitcnt(0);
;         unsigned nloc = b.st[0], nx = b.st[1];
;         if (nloc == 0u) { xcd_barrier_complete(bar, b.x, nloc, nx); b.st[0] = nloc; b.st[1] = nx; }
;         const unsigned old = xb_add(&bar[XB_XSUB(b.x)], 1u);
;         const unsigned gen = old / nloc;
;         if (old + 1u == (gen + 1u) * nloc) {
;             __builtin_amdgcn_fence(__ATOMIC_RELEASE, "agent");
;             asm volatile("s_waitcnt vmcnt(0)" ::: "memory");
;             const unsigned og = xb_add(&bar[XB_TOP], 1u);
;             const unsigned tg = og / nx;
;             if (og + 1u == (tg + 1u) * nx) xb_add(&bar[XB_TOPGEN], 1u);
;             else XB_SPIN(xb_ld(&bar[XB_TOPGEN]) == tg, bar);
;             __builtin_amdgcn_fence(__ATOMIC_ACQUIRE, "agent");
;             xb_add(&bar[XB_XGEN(b.x)], 1u);
;             asm volatile("s_waitcnt vmcnt(0)" ::: "memory");
;         } else {
;             XB_SPIN(xb_ld(&bar[XB_XGEN(b.x)]) == gen, bar);
;             __builtin_amdgcn_fence(__ATOMIC_ACQUIRE, "agent");
;             asm volatile("s_waitcnt vmcnt(0)" ::: "memory");
;         }
;     }
;     __syncthreads();
; }
.LBB0_443:
	s_cmp_lt_i32 s56, 3
	s_waitcnt lgkmcnt(0)
	s_cselect_b64 s[14:15], -1, 0
	s_cmp_gt_i32 s57, 2
	s_cselect_b64 s[0:1], -1, 0
	s_and_b64 s[0:1], s[14:15], s[0:1]
	s_andn2_b64 vcc, exec, s[0:1]
	s_cbranch_vccnz .LBB0_545
	s_and_b64 vcc, exec, s[10:11]
	s_cbranch_vccz .LBB0_498
	s_getreg_b32 s3, hwreg(HW_REG_XCC_ID, 0, 4)
	s_waitcnt vmcnt(0)
	v_cmp_eq_u32_e32 vcc, 0, v178
	s_waitcnt vmcnt(0)
	s_barrier
	s_and_saveexec_b64 s[0:1], vcc
	s_cbranch_execz .LBB0_497
	buffer_inv sc1
	v_mov_b32_e32 v0, 0x23ff0
	ds_read2_b32 v[0:1], v0 offset1:1
	s_and_b32 s98, s3, 15
	s_lshl_b32 s98, s98, 8
	s_add_u32 s98, s54, s98
	s_addc_u32 s99, s55, 0
	s_add_u32 s98, s98, 0x22a3400
	s_addc_u32 s99, s99, 0
	v_mov_b32_e32 v2, 0
	v_mov_b32_e32 v3, 1
	global_atomic_add v4, v2, v3, s[98:99] sc0
	s_add_u32 s100, s54, 0x22a5400
	s_addc_u32 s101, s55, 0
	s_waitcnt vmcnt(0) lgkmcnt(0)
	v_mul_u32_u24_e32 v0, 2, v0
	v_mul_u32_u24_e32 v1, 2, v1
	v_add_u32_e32 v4, 1, v4
	v_cmp_eq_u32_e32 vcc, v4, v0
	s_cbranch_vccz .Lxb_poll_s1
	buffer_wbl2 sc1
	s_waitcnt vmcnt(0)
	global_atomic_add v2, v3, s[100:101]
.Lxb_poll_s1:
	global_load_dword v4, v2, s[100:101] sc1
	s_waitcnt vmcnt(0)
	v_cmp_ge_u32_e32 vcc, v4, v1
	s_cbranch_vccnz .Lxb_done_s1
	s_sleep 1
	s_branch .Lxb_poll_s1
.Lxb_done_s1:
.LBB0_497:
	s_or_b64 exec, exec, s[0:1]
	s_waitcnt lgkmcnt(0)
	s_barrier

; __device__ __forceinline__ unsigned xb_ld(unsigned* p)              { return __hip_atomic_load(p, __ATOMIC_RELAXED, __HIP_MEMORY_SCOPE_AGENT); }
; __device__ __forceinline__ unsigned xb_add(unsigned* p, unsigned v) { return __hip_atomic_fetch_add(p, v, __ATOMIC_RELAXED, __HIP_MEMORY_SCOPE_AGENT); }
; #define XB_SPIN(cond, bar) do { unsigned _sp = 0; while (cond) { __builtin_amdgcn_s_sleep(1); \
;     if ((++_sp & 255u) == 0u) { if (xb_ld(&(bar)[XB_TMO])) break; if (_sp > XB_SPIN_CAP) { atomicAdd(&(bar)[XB_TMO], 1u); break; } } } } while (0)
; __device__ __forceinline__ void xcd_barrier(const XcdBarrier& b) {
;     asm volatile("s_waitcnt vmcnt(0)" ::: "memory");
;     __syncthreads();
;     if (threadIdx.x == 0) {
;         unsigned* bar = b.bar;
;         __builtin_amdgcn_s_waitcnt(0);
;         unsigned nloc = b.st[0], nx = b.st[1];
;         if (nloc == 0u) { xcd_barrier_complete(bar, b.x, nloc, nx); b.st[0] = nloc; b.st[1] = nx; }
;         const unsigned old = xb_add(&bar[XB_XSUB(b.x)], 1u);
;         const unsigned gen = old / nloc;
;         if (old + 1u == (gen + 1u) * nloc) {
;             __builtin_amdgcn_fence(__ATOMIC_RELEASE, "agent");
;             asm volatile("s_waitcnt vmcnt(0)" ::: "memory");
;             const unsigned og = xb_add(&bar[XB_TOP], 1u);
;             const unsigned tg = og / nx;
;             if (og + 1u == (tg + 1u) * nx) xb_add(&bar[XB_TOPGEN], 1u);
;             else XB_SPIN(xb_ld(&bar[XB_TOPGEN]) == tg, bar);
;             __builtin_amdgcn_fence(__ATOMIC_ACQUIRE, "agent");
;             xb_add(&bar[XB_XGEN(b.x)], 1u);
;             asm volatile("s_waitcnt vmcnt(0)" ::: "memory");
;         } else {
;             XB_SPIN(xb_ld(&bar[XB_XGEN(b.x)]) == gen, bar);
;             __builtin_amdgcn_fence(__ATOMIC_ACQUIRE, "agent");
;             asm volatile("s_waitcnt vmcnt(0)" ::: "memory");
;         }
;     }
;     __syncthreads();
; }
.LBB0_545:
	s_cmp_lt_i32 s56, 4
	s_cselect_b64 s[0:1], -1, 0
	s_cmp_gt_i32 s57, 3
	s_cselect_b64 s[4:5], -1, 0
	s_and_b64 s[4:5], s[0:1], s[4:5]
	s_andn2_b64 vcc, exec, s[4:5]
	s_cbranch_vccnz .LBB0_670
	s_andn2_b64 vcc, exec, s[14:15]
	s_cbranch_vccnz .LBB0_558
	s_getreg_b32 s3, hwreg(HW_REG_XCC_ID, 0, 4)
	s_waitcnt vmcnt(0)
	v_cmp_eq_u32_e32 vcc, 0, v178
	s_waitcnt vmcnt(0)
	s_barrier
	s_and_saveexec_b64 s[4:5], vcc
	s_cbranch_execz .LBB0_631
	buffer_inv sc1
	v_mov_b32_e32 v0, 0x23ff0
	ds_read2_b32 v[0:1], v0 offset1:1
	s_and_b32 s98, s3, 15
	s_lshl_b32 s98, s98, 8
	s_add_u32 s98, s54, s98
	s_addc_u32 s99, s55, 0
	s_add_u32 s98, s98, 0x22a3400
	s_addc_u32 s99, s99, 0
	v_mov_b32_e32 v2, 0
	v_mov_b32_e32 v3, 1
	global_atomic_add v4, v2, v3, s[98:99] sc0
	s_add_u32 s100, s54, 0x22a5400
	s_addc_u32 s101, s55, 0
	s_waitcnt vmcnt(0) lgkmcnt(0)
	v_mul_u32_u24_e32 v0, 3, v0
	v_mul_u32_u24_e32 v1, 3, v1
	v_add_u32_e32 v4, 1, v4
	v_cmp_eq_u32_e32 vcc, v4, v0
	s_cbranch_vccz .Lxb_poll_s2
	buffer_wbl2 sc1
	s_waitcnt vmcnt(0)
	global_atomic_add v2, v3, s[100:101]

; __device__ __forceinline__ unsigned xb_ld(unsigned* p)              { return __hip_atomic_load(p, __ATOMIC_RELAXED, __HIP_MEMORY_SCOPE_AGENT); }
; __device__ __forceinline__ unsigned xb_add(unsigned* p, unsigned v) { return __hip_atomic_fetch_add(p, v, __ATOMIC_RELAXED, __HIP_MEMORY_SCOPE_AGENT); }
; #define XB_SPIN(cond, bar) do { unsigned _sp = 0; while (cond) { __builtin_amdgcn_s_sleep(1); \
;     if ((++_sp & 255u) == 0u) { if (xb_ld(&(bar)[XB_TMO])) break; if (_sp > XB_SPIN_CAP) { atomicAdd(&(bar)[XB_TMO], 1u); break; } } } } while (0)
; __device__ __forceinline__ void xcd_barrier(const XcdBarrier& b) {
;     asm volatile("s_waitcnt vmcnt(0)" ::: "memory");
;     __syncthreads();
;     if (threadIdx.x == 0) {
;         unsigned* bar = b.bar;
;         __builtin_amdgcn_s_waitcnt(0);
;         unsigned nloc = b.st[0], nx = b.st[1];
;         if (nloc == 0u) { xcd_barrier_complete(bar, b.x, nloc, nx); b.st[0] = nloc; b.st[1] = nx; }
;         const unsigned old = xb_add(&bar[XB_XSUB(b.x)], 1u);
;         const unsigned gen = old / nloc;
;         if (old + 1u == (gen + 1u) * nloc) {
;             __builtin_amdgcn_fence(__ATOMIC_RELEASE, "agent");
;             asm volatile("s_waitcnt vmcnt(0)" ::: "memory");
;             const unsigned og = xb_add(&bar[XB_TOP], 1u);
;             const unsigned tg = og / nx;
;             if (og + 1u == (tg + 1u) * nx) xb_add(&bar[XB_TOPGEN], 1u);
;             else XB_SPIN(xb_ld(&bar[XB_TOPGEN]) == tg, bar);
;             __builtin_amdgcn_fence(__ATOMIC_ACQUIRE, "agent");
;             xb_add(&bar[XB_XGEN(b.x)], 1u);
;             asm volatile("s_waitcnt vmcnt(0)" ::: "memory");
;         } else {
;             XB_SPIN(xb_ld(&bar[XB_XGEN(b.x)]) == gen, bar);
;             __builtin_amdgcn_fence(__ATOMIC_ACQUIRE, "agent");
;             asm volatile("s_waitcnt vmcnt(0)" ::: "memory");
;         }
;     }
;     __syncthreads();
; }
.Lxb_done_s2:
	s_branch .LBB0_631
	s_add_i32 s6, 0, 0x23ff0
	v_mov_b32_e32 v0, s6
	s_waitcnt vmcnt(0) expcnt(0) lgkmcnt(0)
	ds_read_b32 v2, v0
	s_add_i32 s6, 0, 0x23ff4
	v_mov_b32_e32 v0, s6
	ds_read_b32 v0, v0
	s_and_b32 s3, s3, 15
	s_waitcnt lgkmcnt(1)
	v_cmp_ne_u32_e32 vcc, 0, v2
	s_cbranch_vccnz .LBB0_595
	v_readlane_b32 s6, v252, 0
	s_mul_i32 s33, s6, s58
	s_add_u32 s6, s54, 0x22a2200
	s_addc_u32 s7, s55, 0
	s_add_u32 s8, s54, 0x22a2400
	s_addc_u32 s9, s55, 0
	s_add_u32 s10, s54, 0x22a2500
	s_addc_u32 s11, s55, 0
	s_add_u32 s14, s54, 0x22a2600
	s_addc_u32 s15, s55, 0
	s_add_u32 s24, s54, 0x22a2700
	s_addc_u32 s25, s55, 0
	s_add_u32 s26, s54, 0x22a2800
	s_addc_u32 s27, s55, 0
	s_add_u32 s28, s54, 0x22a2900
	s_addc_u32 s29, s55, 0
	s_add_u32 s30, s54, 0x22a2a00
	s_addc_u32 s31, s55, 0
	s_add_u32 s34, s54, 0x22a2b00
	s_addc_u32 s35, s55, 0
	s_add_u32 s40, s54, 0x22a2c00
	s_addc_u32 s41, s55, 0
	s_add_u32 s42, s54, 0x22a2d00
	s_addc_u32 s43, s55, 0
	s_add_u32 s44, s54, 0x22a2e00
	s_addc_u32 s45, s55, 0
	s_add_u32 s46, s54, 0x22a2f00
	s_addc_u32 s47, s55, 0
	s_add_u32 s60, s54, 0x22a3000
	s_addc_u32 s61, s55, 0
	s_add_u32 s62, s54, 0x22a3100
	s_addc_u32 s63, s55, 0
	s_add_u32 s64, s54, 0x22a3200
	s_addc_u32 s65, s55, 0
	s_add_u32 s66, s54, 0x22a3300
	s_mul_i32 s33, s33, s59
	s_addc_u32 s67, s55, 0
	s_mov_b32 s74, 1
	v_mov_b32_e32 v16, 0
	s_branch .LBB0_551

; __device__ __forceinline__ unsigned xb_ld(unsigned* p)              { return __hip_atomic_load(p, __ATOMIC_RELAXED, __HIP_MEMORY_SCOPE_AGENT); }
; __device__ __forceinline__ unsigned xb_add(unsigned* p, unsigned v) { return __hip_atomic_fetch_add(p, v, __ATOMIC_RELAXED, __HIP_MEMORY_SCOPE_AGENT); }
; #define XB_SPIN(cond, bar) do { unsigned _sp = 0; while (cond) { __builtin_amdgcn_s_sleep(1); \
;     if ((++_sp & 255u) == 0u) { if (xb_ld(&(bar)[XB_TMO])) break; if (_sp > XB_SPIN_CAP) { atomicAdd(&(bar)[XB_TMO], 1u); break; } } } } while (0)
; __device__ __forceinline__ void xcd_barrier(const XcdBarrier& b) {
;     asm volatile("s_waitcnt vmcnt(0)" ::: "memory");
;     __syncthreads();
;     if (threadIdx.x == 0) {
;         unsigned* bar = b.bar;
;         __builtin_amdgcn_s_waitcnt(0);
;         unsigned nloc = b.st[0], nx = b.st[1];
;         if (nloc == 0u) { xcd_barrier_complete(bar, b.x, nloc, nx); b.st[0] = nloc; b.st[1] = nx; }
;         const unsigned old = xb_add(&bar[XB_XSUB(b.x)], 1u);
;         const unsigned gen = old / nloc;
;         if (old + 1u == (gen + 1u) * nloc) {
;             __builtin_amdgcn_fence(__ATOMIC_RELEASE, "agent");
;             asm volatile("s_waitcnt vmcnt(0)" ::: "memory");
;             const unsigned og = xb_add(&bar[XB_TOP], 1u);
;             const unsigned tg = og / nx;
;             if (og + 1u == (tg + 1u) * nx) xb_add(&bar[XB_TOPGEN], 1u);
;             else XB_SPIN(xb_ld(&bar[XB_TOPGEN]) == tg, bar);
;             __builtin_amdgcn_fence(__ATOMIC_ACQUIRE, "agent");
;             xb_add(&bar[XB_XGEN(b.x)], 1u);
;             asm volatile("s_waitcnt vmcnt(0)" ::: "memory");
;         } else {
;             XB_SPIN(xb_ld(&bar[XB_XGEN(b.x)]) == gen, bar);
;             __builtin_amdgcn_fence(__ATOMIC_ACQUIRE, "agent");
;             asm volatile("s_waitcnt vmcnt(0)" ::: "memory");
;         }
;     }
;     __syncthreads();
; }
.LBB0_670:
	s_cmp_lt_i32 s56, 5
	s_cselect_b64 s[14:15], -1, 0
	s_cmp_gt_i32 s57, 4
	s_cselect_b64 s[4:5], -1, 0
	s_and_b64 s[4:5], s[14:15], s[4:5]
	s_andn2_b64 vcc, exec, s[4:5]
	s_cbranch_vccnz .LBB0_745
	s_andn2_b64 vcc, exec, s[0:1]
	s_cbranch_vccnz .LBB0_725
	s_getreg_b32 s3, hwreg(HW_REG_XCC_ID, 0, 4)
	s_waitcnt vmcnt(0)
	v_cmp_eq_u32_e32 vcc, 0, v178
	s_waitcnt vmcnt(0)
	s_barrier
	s_and_saveexec_b64 s[0:1], vcc
	s_cbranch_execz .LBB0_724
	buffer_inv sc1
	v_mov_b32_e32 v0, 0x23ff0
	ds_read2_b32 v[0:1], v0 offset1:1
	s_and_b32 s98, s3, 15
	s_lshl_b32 s98, s98, 8
	s_add_u32 s98, s54, s98
	s_addc_u32 s99, s55, 0
	s_add_u32 s98, s98, 0x22a3400
	s_addc_u32 s99, s99, 0
	v_mov_b32_e32 v2, 0
	v_mov_b32_e32 v3, 1
	global_atomic_add v4, v2, v3, s[98:99] sc0
	s_add_u32 s100, s54, 0x22a5400
	s_addc_u32 s101, s55, 0
	s_waitcnt vmcnt(0) lgkmcnt(0)
	v_mul_u32_u24_e32 v0, 4, v0
	v_mul_u32_u24_e32 v1, 4, v1
	v_add_u32_e32 v4, 1, v4
	v_cmp_eq_u32_e32 vcc, v4, v0
	s_cbranch_vccz .Lxb_poll_s3
	buffer_wbl2 sc1
	s_waitcnt vmcnt(0)
	global_atomic_add v2, v3, s[100:101]

; __device__ __forceinline__ unsigned xb_ld(unsigned* p)              { return __hip_atomic_load(p, __ATOMIC_RELAXED, __HIP_MEMORY_SCOPE_AGENT); }
; __device__ __forceinline__ unsigned xb_add(unsigned* p, unsigned v) { return __hip_atomic_fetch_add(p, v, __ATOMIC_RELAXED, __HIP_MEMORY_SCOPE_AGENT); }
; #define XB_SPIN(cond, bar) do { unsigned _sp = 0; while (cond) { __builtin_amdgcn_s_sleep(1); \
;     if ((++_sp & 255u) == 0u) { if (xb_ld(&(bar)[XB_TMO])) break; if (_sp > XB_SPIN_CAP) { atomicAdd(&(bar)[XB_TMO], 1u); break; } } } } while (0)
; __device__ __forceinline__ void xcd_barrier(const XcdBarrier& b) {
;     asm volatile("s_waitcnt vmcnt(0)" ::: "memory");
;     __syncthreads();
;     if (threadIdx.x == 0) {
;         unsigned* bar = b.bar;
;         __builtin_amdgcn_s_waitcnt(0);
;         unsigned nloc = b.st[0], nx = b.st[1];
;         if (nloc == 0u) { xcd_barrier_complete(bar, b.x, nloc, nx); b.st[0] = nloc; b.st[1] = nx; }
;         const unsigned old = xb_add(&bar[XB_XSUB(b.x)], 1u);
;         const unsigned gen = old / nloc;
;         if (old + 1u == (gen + 1u) * nloc) {
;             __builtin_amdgcn_fence(__ATOMIC_RELEASE, "agent");
;             asm volatile("s_waitcnt vmcnt(0)" ::: "memory");
;             const unsigned og = xb_add(&bar[XB_TOP], 1u);
;             const unsigned tg = og / nx;
;             if (og + 1u == (tg + 1u) * nx) xb_add(&bar[XB_TOPGEN], 1u);
;             else XB_SPIN(xb_ld(&bar[XB_TOPGEN]) == tg, bar);
;             __builtin_amdgcn_fence(__ATOMIC_ACQUIRE, "agent");
;             xb_add(&bar[XB_XGEN(b.x)], 1u);
;             asm volatile("s_waitcnt vmcnt(0)" ::: "memory");
;         } else {
;             XB_SPIN(xb_ld(&bar[XB_XGEN(b.x)]) == gen, bar);
;             __builtin_amdgcn_fence(__ATOMIC_ACQUIRE, "agent");
;             asm volatile("s_waitcnt vmcnt(0)" ::: "memory");
;         }
;     }
;     __syncthreads();
; }
.LBB0_745:
	s_cmp_lt_i32 s56, 6
	s_cselect_b64 s[0:1], -1, 0
	s_cmp_gt_i32 s57, 5
	s_cselect_b64 s[4:5], -1, 0
	s_and_b64 s[0:1], s[0:1], s[4:5]
	s_andn2_b64 vcc, exec, s[0:1]
	s_cbranch_vccnz .LBB0_841
	s_andn2_b64 vcc, exec, s[14:15]
	s_cbranch_vccnz .LBB0_800
	s_getreg_b32 s3, hwreg(HW_REG_XCC_ID, 0, 4)
	s_waitcnt vmcnt(0)
	v_cmp_eq_u32_e32 vcc, 0, v178
	s_waitcnt vmcnt(0)
	s_barrier
	s_and_saveexec_b64 s[0:1], vcc
	s_cbranch_execz .LBB0_799
	buffer_inv sc1
	v_mov_b32_e32 v0, 0x23ff0
	ds_read2_b32 v[0:1], v0 offset1:1
	s_and_b32 s98, s3, 15
	s_lshl_b32 s98, s98, 8
	s_add_u32 s98, s54, s98
	s_addc_u32 s99, s55, 0
	s_add_u32 s98, s98, 0x22a3400
	s_addc_u32 s99, s99, 0
	v_mov_b32_e32 v2, 0
	v_mov_b32_e32 v3, 1
	global_atomic_add v4, v2, v3, s[98:99] sc0
	s_add_u32 s100, s54, 0x22a5400
	s_addc_u32 s101, s55, 0
	s_waitcnt vmcnt(0) lgkmcnt(0)
	v_mul_u32_u24_e32 v0, 5, v0
	v_mul_u32_u24_e32 v1, 5, v1
	v_add_u32_e32 v4, 1, v4
	v_cmp_eq_u32_e32 vcc, v4, v0
	s_cbranch_vccz .Lxb_poll_s4
	buffer_wbl2 sc1
	s_waitcnt vmcnt(0)
	global_atomic_add v2, v3, s[100:101]

; __device__ __forceinline__ unsigned xb_ld(unsigned* p)              { return __hip_atomic_load(p, __ATOMIC_RELAXED, __HIP_MEMORY_SCOPE_AGENT); }
; __device__ __forceinline__ unsigned xb_add(unsigned* p, unsigned v) { return __hip_atomic_fetch_add(p, v, __ATOMIC_RELAXED, __HIP_MEMORY_SCOPE_AGENT); }
; #define XB_SPIN(cond, bar) do { unsigned _sp = 0; while (cond) { __builtin_amdgcn_s_sleep(1); \
;     if ((++_sp & 255u) == 0u) { if (xb_ld(&(bar)[XB_TMO])) break; if (_sp > XB_SPIN_CAP) { atomicAdd(&(bar)[XB_TMO], 1u); break; } } } } while (0)
; #define PH(k) if (a.ph_lo <= (k) && (k) < a.ph_hi) { if ((k) > a.ph_lo && (k) != 6) SEAM(k);
; __device__ __forceinline__ void xcd_barrier(const XcdBarrier& b) {
;     asm volatile("s_waitcnt vmcnt(0)" ::: "memory");
;     __syncthreads();
;     if (threadIdx.x == 0) {
;         unsigned* bar = b.bar;
;         __builtin_amdgcn_s_waitcnt(0);
;         unsigned nloc = b.st[0], nx = b.st[1];
;         if (nloc == 0u) { xcd_barrier_complete(bar, b.x, nloc, nx); b.st[0] = nloc; b.st[1] = nx; }
;         const unsigned old = xb_add(&bar[XB_XSUB(b.x)], 1u);
;         const unsigned gen = old / nloc;
;         if (old + 1u == (gen + 1u) * nloc) {
;             __builtin_amdgcn_fence(__ATOMIC_RELEASE, "agent");
;             asm volatile("s_waitcnt vmcnt(0)" ::: "memory");
;             const unsigned og = xb_add(&bar[XB_TOP], 1u);
;             const unsigned tg = og / nx;
;             if (og + 1u == (tg + 1u) * nx) xb_add(&bar[XB_TOPGEN], 1u);
;             else XB_SPIN(xb_ld(&bar[XB_TOPGEN]) == tg, bar);
;             __builtin_amdgcn_fence(__ATOMIC_ACQUIRE, "agent");
;             xb_add(&bar[XB_XGEN(b.x)], 1u);
;             asm volatile("s_waitcnt vmcnt(0)" ::: "memory");
;         } else {
;             XB_SPIN(xb_ld(&bar[XB_XGEN(b.x)]) == gen, bar);
;             __builtin_amdgcn_fence(__ATOMIC_ACQUIRE, "agent");
;             asm volatile("s_waitcnt vmcnt(0)" ::: "memory");
;         }
;     }
;     __syncthreads();
; }
; __global__ void __launch_bounds__(512) fwd_kernel(Args a) {
;     ...
;     PH(7) { GEMM_N1024(EpiN1024<2>, A_GA, WS_WOUT, MP, 1024, 0, G, bx, (bf16_t*)(a.ws + A_GB), nullptr, (float*)(a.ws + WS_RSS1)); } PHEND
.LBB0_841:
	s_cmp_lt_i32 s56, 8
	s_cselect_b64 s[6:7], -1, 0
	s_cmp_gt_i32 s57, 7
	s_cselect_b64 s[0:1], -1, 0
	s_and_b64 s[0:1], s[6:7], s[0:1]
	s_andn2_b64 vcc, exec, s[0:1]
	s_cbranch_vccnz .LBB0_934
	s_cmp_gt_i32 s56, 6
	s_cbranch_scc1 .LBB0_896
	s_getreg_b32 s3, hwreg(HW_REG_XCC_ID, 0, 4)
	s_waitcnt vmcnt(0)
	v_cmp_eq_u32_e32 vcc, 0, v178
	s_waitcnt vmcnt(0)
	s_barrier
	s_and_saveexec_b64 s[0:1], vcc
	s_cbranch_execz .LBB0_895
	buffer_inv sc1
	v_mov_b32_e32 v0, 0x23ff0
	ds_read2_b32 v[0:1], v0 offset1:1
	s_and_b32 s98, s3, 15
	s_lshl_b32 s98, s98, 8
	s_add_u32 s98, s54, s98
	s_addc_u32 s99, s55, 0
	s_add_u32 s98, s98, 0x22a3400
	s_addc_u32 s99, s99, 0
	v_mov_b32_e32 v2, 0
	v_mov_b32_e32 v3, 1
	global_atomic_add v4, v2, v3, s[98:99] sc0
	s_add_u32 s100, s54, 0x22a5400
	s_addc_u32 s101, s55, 0
	s_waitcnt vmcnt(0) lgkmcnt(0)
	v_mul_u32_u24_e32 v0, 6, v0
	v_mul_u32_u24_e32 v1, 6, v1
	v_add_u32_e32 v4, 1, v4
	v_cmp_eq_u32_e32 vcc, v4, v0
	s_cbranch_vccz .Lxb_poll_s5
	buffer_wbl2 sc1
	s_waitcnt vmcnt(0)
	global_atomic_add v2, v3, s[100:101]

; __device__ __forceinline__ unsigned xb_ld(unsigned* p)              { return __hip_atomic_load(p, __ATOMIC_RELAXED, __HIP_MEMORY_SCOPE_AGENT); }
; __device__ __forceinline__ unsigned xb_add(unsigned* p, unsigned v) { return __hip_atomic_fetch_add(p, v, __ATOMIC_RELAXED, __HIP_MEMORY_SCOPE_AGENT); }
; #define XB_SPIN(cond, bar) do { unsigned _sp = 0; while (cond) { __builtin_amdgcn_s_sleep(1); \
;     if ((++_sp & 255u) == 0u) { if (xb_ld(&(bar)[XB_TMO])) break; if (_sp > XB_SPIN_CAP) { atomicAdd(&(bar)[XB_TMO], 1u); break; } } } } while (0)
; __device__ __forceinline__ void xcd_barrier(const XcdBarrier& b) {
;     asm volatile("s_waitcnt vmcnt(0)" ::: "memory");
;     __syncthreads();
;     if (threadIdx.x == 0) {
;         unsigned* bar = b.bar;
;         __builtin_amdgcn_s_waitcnt(0);
;         unsigned nloc = b.st[0], nx = b.st[1];
;         if (nloc == 0u) { xcd_barrier_complete(bar, b.x, nloc, nx); b.st[0] = nloc; b.st[1] = nx; }
;         const unsigned old = xb_add(&bar[XB_XSUB(b.x)], 1u);
;         const unsigned gen = old / nloc;
;         if (old + 1u == (gen + 1u) * nloc) {
;             __builtin_amdgcn_fence(__ATOMIC_RELEASE, "agent");
;             asm volatile("s_waitcnt vmcnt(0)" ::: "memory");
;             const unsigned og = xb_add(&bar[XB_TOP], 1u);
;             const unsigned tg = og / nx;
;             if (og + 1u == (tg + 1u) * nx) xb_add(&bar[XB_TOPGEN], 1u);
;             else XB_SPIN(xb_ld(&bar[XB_TOPGEN]) == tg, bar);
;             __builtin_amdgcn_fence(__ATOMIC_ACQUIRE, "agent");
;             xb_add(&bar[XB_XGEN(b.x)], 1u);
;             asm volatile("s_waitcnt vmcnt(0)" ::: "memory");
;         } else {
;             XB_SPIN(xb_ld(&bar[XB_XGEN(b.x)]) == gen, bar);
;             __builtin_amdgcn_fence(__ATOMIC_ACQUIRE, "agent");
;             asm volatile("s_waitcnt vmcnt(0)" ::: "memory");
;         }
;     }
;     __syncthreads();
; }
; __global__ void __launch_bounds__(512) fwd_kernel(Args a) {
;     ...
;     PH(8) {
;         if (G >= 32 && bx < 16) GEMM_N1024(EpiN1024<2>, A_GA, WS_WOUT, MS, 1024, MP, 16, bx, (bf16_t*)(a.ws + A_GB), nullptr, (float*)(a.ws + WS_RSS1));
;         else if (G >= 32) row_pass1(a, 0, MP, gw - 128, NGW - 128, lane);
;         else { row_pass1(a, 0, MP, gw, NGW, lane); GEMM_N1024(EpiN1024<2>, A_GA, WS_WOUT, MS, 1024, MP, G, bx, (bf16_t*)(a.ws + A_GB), nullptr, (float*)(a.ws + WS_RSS1)); }
;     } PHEND
.LBB0_934:
	s_cmp_lt_i32 s56, 9
	s_cselect_b64 s[4:5], -1, 0
	s_cmp_gt_i32 s57, 8
	s_cselect_b64 s[0:1], -1, 0
	s_and_b64 s[0:1], s[4:5], s[0:1]
	s_andn2_b64 vcc, exec, s[0:1]
	s_cbranch_vccnz .LBB0_1079
	s_andn2_b64 vcc, exec, s[6:7]
	s_cbranch_vccnz .LBB0_989
	s_getreg_b32 s3, hwreg(HW_REG_XCC_ID, 0, 4)
	s_waitcnt vmcnt(0)
	v_cmp_eq_u32_e32 vcc, 0, v178
	s_waitcnt vmcnt(0) lgkmcnt(0)
	s_barrier
	s_and_saveexec_b64 s[0:1], vcc
	s_cbranch_execz .LBB0_988
	buffer_inv sc1
	v_mov_b32_e32 v0, 0x23ff0
	ds_read2_b32 v[0:1], v0 offset1:1
	s_and_b32 s98, s3, 15
	s_lshl_b32 s98, s98, 8
	s_add_u32 s98, s54, s98
	s_addc_u32 s99, s55, 0
	s_add_u32 s98, s98, 0x22a3400
	s_addc_u32 s99, s99, 0
	v_mov_b32_e32 v2, 0
	v_mov_b32_e32 v3, 1
	global_atomic_add v4, v2, v3, s[98:99] sc0
	s_add_u32 s100, s54, 0x22a5400
	s_addc_u32 s101, s55, 0
	s_waitcnt vmcnt(0) lgkmcnt(0)
	v_mul_u32_u24_e32 v0, 7, v0
	v_mul_u32_u24_e32 v1, 7, v1
	v_add_u32_e32 v4, 1, v4
	v_cmp_eq_u32_e32 vcc, v4, v0
	s_cbranch_vccz .Lxb_poll_s6
	buffer_wbl2 sc1
	s_waitcnt vmcnt(0)
	global_atomic_add v2, v3, s[100:101]

; __device__ __forceinline__ unsigned xb_ld(unsigned* p)              { return __hip_atomic_load(p, __ATOMIC_RELAXED, __HIP_MEMORY_SCOPE_AGENT); }
; __device__ __forceinline__ unsigned xb_add(unsigned* p, unsigned v) { return __hip_atomic_fetch_add(p, v, __ATOMIC_RELAXED, __HIP_MEMORY_SCOPE_AGENT); }
; #define XB_SPIN(cond, bar) do { unsigned _sp = 0; while (cond) { __builtin_amdgcn_s_sleep(1); \
;     if ((++_sp & 255u) == 0u) { if (xb_ld(&(bar)[XB_TMO])) break; if (_sp > XB_SPIN_CAP) { atomicAdd(&(bar)[XB_TMO], 1u); break; } } } } while (0)
; #define PH(k) if (a.ph_lo <= (k) && (k) < a.ph_hi) { if ((k) > a.ph_lo && (k) != 6) SEAM(k);
; __device__ __forceinline__ void xcd_barrier(const XcdBarrier& b) {
;     asm volatile("s_waitcnt vmcnt(0)" ::: "memory");
;     __syncthreads();
;     if (threadIdx.x == 0) {
;         unsigned* bar = b.bar;
;         __builtin_amdgcn_s_waitcnt(0);
;         unsigned nloc = b.st[0], nx = b.st[1];
;         if (nloc == 0u) { xcd_barrier_complete(bar, b.x, nloc, nx); b.st[0] = nloc; b.st[1] = nx; }
;         const unsigned old = xb_add(&bar[XB_XSUB(b.x)], 1u);
;         const unsigned gen = old / nloc;
;         if (old + 1u == (gen + 1u) * nloc) {
;             __builtin_amdgcn_fence(__ATOMIC_RELEASE, "agent");
;             asm volatile("s_waitcnt vmcnt(0)" ::: "memory");
;             const unsigned og = xb_add(&bar[XB_TOP], 1u);
;             const unsigned tg = og / nx;
;             if (og + 1u == (tg + 1u) * nx) xb_add(&bar[XB_TOPGEN], 1u);
;             else XB_SPIN(xb_ld(&bar[XB_TOPGEN]) == tg, bar);
;             __builtin_amdgcn_fence(__ATOMIC_ACQUIRE, "agent");
;             xb_add(&bar[XB_XGEN(b.x)], 1u);
;             asm volatile("s_waitcnt vmcnt(0)" ::: "memory");
;         } else {
;             XB_SPIN(xb_ld(&bar[XB_XGEN(b.x)]) == gen, bar);
;             __builtin_amdgcn_fence(__ATOMIC_ACQUIRE, "agent");
;             asm volatile("s_waitcnt vmcnt(0)" ::: "memory");
;         }
;     }
;     __syncthreads();
; }
; __global__ void __launch_bounds__(512) fwd_kernel(Args a) {
;     ...
;     PH(9) { row_pass1(a, MP, MT, gw, NGW, lane); } PHEND
.LBB0_1079:
	s_cmp_lt_i32 s56, 10
	s_cselect_b64 s[6:7], -1, 0
	s_cmp_gt_i32 s57, 9
	s_cselect_b64 s[0:1], -1, 0
	s_and_b64 s[0:1], s[6:7], s[0:1]
	s_andn2_b64 vcc, exec, s[0:1]
	s_cbranch_vccnz .LBB0_1139
	s_andn2_b64 vcc, exec, s[4:5]
	s_cbranch_vccnz .LBB0_1134
	s_getreg_b32 s3, hwreg(HW_REG_XCC_ID, 0, 4)
	s_waitcnt vmcnt(0)
	v_cmp_eq_u32_e32 vcc, 0, v178
	s_waitcnt vmcnt(0) lgkmcnt(0)
	s_barrier
	s_and_saveexec_b64 s[0:1], vcc
	s_cbranch_execz .LBB0_1133
	buffer_inv sc1
	v_mov_b32_e32 v0, 0x23ff0
	ds_read2_b32 v[0:1], v0 offset1:1
	s_and_b32 s98, s3, 15
	s_lshl_b32 s98, s98, 8
	s_add_u32 s98, s54, s98
	s_addc_u32 s99, s55, 0
	s_add_u32 s98, s98, 0x22a3400
	s_addc_u32 s99, s99, 0
	v_mov_b32_e32 v2, 0
	v_mov_b32_e32 v3, 1
	global_atomic_add v4, v2, v3, s[98:99] sc0
	s_add_u32 s100, s54, 0x22a5400
	s_addc_u32 s101, s55, 0
	s_waitcnt vmcnt(0) lgkmcnt(0)
	v_mul_u32_u24_e32 v0, 8, v0
	v_mul_u32_u24_e32 v1, 8, v1
	v_add_u32_e32 v4, 1, v4
	v_cmp_eq_u32_e32 vcc, v4, v0
	s_cbranch_vccz .Lxb_poll_s7
	buffer_wbl2 sc1
	s_waitcnt vmcnt(0)
	global_atomic_add v2, v3, s[100:101]

; __device__ __forceinline__ unsigned xb_ld(unsigned* p)              { return __hip_atomic_load(p, __ATOMIC_RELAXED, __HIP_MEMORY_SCOPE_AGENT); }
; __device__ __forceinline__ unsigned xb_add(unsigned* p, unsigned v) { return __hip_atomic_fetch_add(p, v, __ATOMIC_RELAXED, __HIP_MEMORY_SCOPE_AGENT); }
; #define XB_SPIN(cond, bar) do { unsigned _sp = 0; while (cond) { __builtin_amdgcn_s_sleep(1); \
;     if ((++_sp & 255u) == 0u) { if (xb_ld(&(bar)[XB_TMO])) break; if (_sp > XB_SPIN_CAP) { atomicAdd(&(bar)[XB_TMO], 1u); break; } } } } while (0)
; #define PH(k) if (a.ph_lo <= (k) && (k) < a.ph_hi) { if ((k) > a.ph_lo && (k) != 6) SEAM(k);
; __device__ __forceinline__ void xcd_barrier(const XcdBarrier& b) {
;     asm volatile("s_waitcnt vmcnt(0)" ::: "memory");
;     __syncthreads();
;     if (threadIdx.x == 0) {
;         unsigned* bar = b.bar;
;         __builtin_amdgcn_s_waitcnt(0);
;         unsigned nloc = b.st[0], nx = b.st[1];
;         if (nloc == 0u) { xcd_barrier_complete(bar, b.x, nloc, nx); b.st[0] = nloc; b.st[1] = nx; }
;         const unsigned old = xb_add(&bar[XB_XSUB(b.x)], 1u);
;         const unsigned gen = old / nloc;
;         if (old + 1u == (gen + 1u) * nloc) {
;             __builtin_amdgcn_fence(__ATOMIC_RELEASE, "agent");
;             asm volatile("s_waitcnt vmcnt(0)" ::: "memory");
;             const unsigned og = xb_add(&bar[XB_TOP], 1u);
;             const unsigned tg = og / nx;
;             if (og + 1u == (tg + 1u) * nx) xb_add(&bar[XB_TOPGEN], 1u);
;             else XB_SPIN(xb_ld(&bar[XB_TOPGEN]) == tg, bar);
;             __builtin_amdgcn_fence(__ATOMIC_ACQUIRE, "agent");
;             xb_add(&bar[XB_XGEN(b.x)], 1u);
;             asm volatile("s_waitcnt vmcnt(0)" ::: "memory");
;         } else {
;             XB_SPIN(xb_ld(&bar[XB_XGEN(b.x)]) == gen, bar);
;             __builtin_amdgcn_fence(__ATOMIC_ACQUIRE, "agent");
;             asm volatile("s_waitcnt vmcnt(0)" ::: "memory");
;         }
;     }
;     __syncthreads();
; }
; __global__ void __launch_bounds__(512) fwd_kernel(Args a) {
;     ...
;     PH(10) {
;         pg8::Gemm g{(const bf16_t*)(a.ws + A_RB), (const bf16_t*)(a.ws + WS_WGU), MT, NGU, 1024}; pg8::StaticOrder S; S.init(MT, NGU, G, bx);
;         EpiSwiglu E{(bf16_t*)(a.ws + A_HID)}; pg8::gemm_phase<EpiSwiglu, pg8::StaticOrder, true, true>(lds, g, S, E);
;     } PHEND
.LBB0_1139:
	s_cmp_lt_i32 s56, 11
	s_cselect_b64 s[4:5], -1, 0
	s_cmp_gt_i32 s57, 10
	s_cselect_b64 s[0:1], -1, 0
	s_and_b64 s[0:1], s[4:5], s[0:1]
	s_andn2_b64 vcc, exec, s[0:1]
	s_cbranch_vccnz .LBB0_1210
	s_andn2_b64 vcc, exec, s[6:7]
	s_cbranch_vccnz .LBB0_1194
	s_getreg_b32 s3, hwreg(HW_REG_XCC_ID, 0, 4)
	s_waitcnt vmcnt(0)
	v_cmp_eq_u32_e32 vcc, 0, v178
	s_waitcnt vmcnt(0) lgkmcnt(0)
	s_barrier
	s_and_saveexec_b64 s[0:1], vcc
	s_cbranch_execz .LBB0_1193
	buffer_inv sc1
	v_mov_b32_e32 v0, 0x23ff0
	ds_read2_b32 v[0:1], v0 offset1:1
	s_and_b32 s98, s3, 15
	s_lshl_b32 s98, s98, 8
	s_add_u32 s98, s54, s98
	s_addc_u32 s99, s55, 0
	s_add_u32 s98, s98, 0x22a3400
	s_addc_u32 s99, s99, 0
	v_mov_b32_e32 v2, 0
	v_mov_b32_e32 v3, 1
	global_atomic_add v4, v2, v3, s[98:99] sc0
	s_add_u32 s100, s54, 0x22a5400
	s_addc_u32 s101, s55, 0
	s_waitcnt vmcnt(0) lgkmcnt(0)
	v_mul_u32_u24_e32 v0, 9, v0
	v_mul_u32_u24_e32 v1, 9, v1
	v_add_u32_e32 v4, 1, v4
	v_cmp_eq_u32_e32 vcc, v4, v0
	s_cbranch_vccz .Lxb_poll_s8
	buffer_wbl2 sc1
	s_waitcnt vmcnt(0)
	global_atomic_add v2, v3, s[100:101]

; __device__ __forceinline__ unsigned xb_ld(unsigned* p)              { return __hip_atomic_load(p, __ATOMIC_RELAXED, __HIP_MEMORY_SCOPE_AGENT); }
; __device__ __forceinline__ unsigned xb_add(unsigned* p, unsigned v) { return __hip_atomic_fetch_add(p, v, __ATOMIC_RELAXED, __HIP_MEMORY_SCOPE_AGENT); }
; #define XB_SPIN(cond, bar) do { unsigned _sp = 0; while (cond) { __builtin_amdgcn_s_sleep(1); \
;     if ((++_sp & 255u) == 0u) { if (xb_ld(&(bar)[XB_TMO])) break; if (_sp > XB_SPIN_CAP) { atomicAdd(&(bar)[XB_TMO], 1u); break; } } } } while (0)
; #define PH(k) if (a.ph_lo <= (k) && (k) < a.ph_hi) { if ((k) > a.ph_lo && (k) != 6) SEAM(k);
; __device__ __forceinline__ void xcd_barrier(const XcdBarrier& b) {
;     asm volatile("s_waitcnt vmcnt(0)" ::: "memory");
;     __syncthreads();
;     if (threadIdx.x == 0) {
;         unsigned* bar = b.bar;
;         __builtin_amdgcn_s_waitcnt(0);
;         unsigned nloc = b.st[0], nx = b.st[1];
;         if (nloc == 0u) { xcd_barrier_complete(bar, b.x, nloc, nx); b.st[0] = nloc; b.st[1] = nx; }
;         const unsigned old = xb_add(&bar[XB_XSUB(b.x)], 1u);
;         const unsigned gen = old / nloc;
;         if (old + 1u == (gen + 1u) * nloc) {
;             __builtin_amdgcn_fence(__ATOMIC_RELEASE, "agent");
;             asm volatile("s_waitcnt vmcnt(0)" ::: "memory");
;             const unsigned og = xb_add(&bar[XB_TOP], 1u);
;             const unsigned tg = og / nx;
;             if (og + 1u == (tg + 1u) * nx) xb_add(&bar[XB_TOPGEN], 1u);
;             else XB_SPIN(xb_ld(&bar[XB_TOPGEN]) == tg, bar);
;             __builtin_amdgcn_fence(__ATOMIC_ACQUIRE, "agent");
;             xb_add(&bar[XB_XGEN(b.x)], 1u);
;             asm volatile("s_waitcnt vmcnt(0)" ::: "memory");
;         } else {
;             XB_SPIN(xb_ld(&bar[XB_XGEN(b.x)]) == gen, bar);
;             __builtin_amdgcn_fence(__ATOMIC_ACQUIRE, "agent");
;             asm volatile("s_waitcnt vmcnt(0)" ::: "memory");
;         }
;     }
;     __syncthreads();
; }
; __global__ void __launch_bounds__(512) fwd_kernel(Args a) {
;     ...
;     PH(11) { GEMM_N1024(EpiN1024<2>, A_HID, WS_WDN, MP, DFF, 0, G, bx, (bf16_t*)(a.ws + A_GA), nullptr, (float*)(a.ws + WS_RSS2)); } PHEND
.LBB0_1210:
	s_cmp_lt_i32 s56, 12
	s_cselect_b64 s[10:11], -1, 0
	s_cmp_gt_i32 s57, 11
	s_cselect_b64 s[0:1], -1, 0
	s_and_b64 s[0:1], s[10:11], s[0:1]
	s_andn2_b64 vcc, exec, s[0:1]
	s_cbranch_vccnz .LBB0_1307
	s_andn2_b64 vcc, exec, s[4:5]
	s_cbranch_vccnz .LBB0_1265
	s_getreg_b32 s3, hwreg(HW_REG_XCC_ID, 0, 4)
	s_waitcnt vmcnt(0)
	v_cmp_eq_u32_e32 vcc, 0, v178
	s_waitcnt vmcnt(0) lgkmcnt(0)
	s_barrier
	s_and_saveexec_b64 s[0:1], vcc
	s_cbranch_execz .LBB0_1264
	buffer_inv sc1
	v_mov_b32_e32 v0, 0x23ff0
	ds_read2_b32 v[0:1], v0 offset1:1
	s_and_b32 s98, s3, 15
	s_lshl_b32 s98, s98, 8
	s_add_u32 s98, s54, s98
	s_addc_u32 s99, s55, 0
	s_add_u32 s98, s98, 0x22a3400
	s_addc_u32 s99, s99, 0
	v_mov_b32_e32 v2, 0
	v_mov_b32_e32 v3, 1
	global_atomic_add v4, v2, v3, s[98:99] sc0
	s_add_u32 s100, s54, 0x22a5400
	s_addc_u32 s101, s55, 0
	s_waitcnt vmcnt(0) lgkmcnt(0)
	v_mul_u32_u24_e32 v0, 10, v0
	v_mul_u32_u24_e32 v1, 10, v1
	v_add_u32_e32 v4, 1, v4
	v_cmp_eq_u32_e32 vcc, v4, v0
	s_cbranch_vccz .Lxb_poll_s9
	buffer_wbl2 sc1
	s_waitcnt vmcnt(0)
	global_atomic_add v2, v3, s[100:101]

; __device__ __forceinline__ unsigned xb_ld(unsigned* p)              { return __hip_atomic_load(p, __ATOMIC_RELAXED, __HIP_MEMORY_SCOPE_AGENT); }
; __device__ __forceinline__ unsigned xb_add(unsigned* p, unsigned v) { return __hip_atomic_fetch_add(p, v, __ATOMIC_RELAXED, __HIP_MEMORY_SCOPE_AGENT); }
; #define XB_SPIN(cond, bar) do { unsigned _sp = 0; while (cond) { __builtin_amdgcn_s_sleep(1); \
;     if ((++_sp & 255u) == 0u) { if (xb_ld(&(bar)[XB_TMO])) break; if (_sp > XB_SPIN_CAP) { atomicAdd(&(bar)[XB_TMO], 1u); break; } } } } while (0)
; __device__ __forceinline__ void xcd_barrier(const XcdBarrier& b) {
;     asm volatile("s_waitcnt vmcnt(0)" ::: "memory");
;     __syncthreads();
;     if (threadIdx.x == 0) {
;         unsigned* bar = b.bar;
;         __builtin_amdgcn_s_waitcnt(0);
;         unsigned nloc = b.st[0], nx = b.st[1];
;         if (nloc == 0u) { xcd_barrier_complete(bar, b.x, nloc, nx); b.st[0] = nloc; b.st[1] = nx; }
;         const unsigned old = xb_add(&bar[XB_XSUB(b.x)], 1u);
;         const unsigned gen = old / nloc;
;         if (old + 1u == (gen + 1u) * nloc) {
;             __builtin_amdgcn_fence(__ATOMIC_RELEASE, "agent");
;             asm volatile("s_waitcnt vmcnt(0)" ::: "memory");
;             const unsigned og = xb_add(&bar[XB_TOP], 1u);
;             const unsigned tg = og / nx;
;             if (og + 1u == (tg + 1u) * nx) xb_add(&bar[XB_TOPGEN], 1u);
;             else XB_SPIN(xb_ld(&bar[XB_TOPGEN]) == tg, bar);
;             __builtin_amdgcn_fence(__ATOMIC_ACQUIRE, "agent");
;             xb_add(&bar[XB_XGEN(b.x)], 1u);
;             asm volatile("s_waitcnt vmcnt(0)" ::: "memory");
;         } else {
;             XB_SPIN(xb_ld(&bar[XB_XGEN(b.x)]) == gen, bar);
;             __builtin_amdgcn_fence(__ATOMIC_ACQUIRE, "agent");
;             asm volatile("s_waitcnt vmcnt(0)" ::: "memory");
;         }
;     }
;     __syncthreads();
; }
; __global__ void __launch_bounds__(512) fwd_kernel(Args a) {
;     ...
;     PH(12) {
;         if (G >= 32 && bx < 16) GEMM_N1024(EpiN1024<2>, A_HID, WS_WDN, MS, DFF, MP, 16, bx, (bf16_t*)(a.ws + A_GA), nullptr, (float*)(a.ws + WS_RSS2));
;         else if (G >= 32) row_pass2(a, 0, MP, gw - 128, NGW - 128, lane);
;         else { row_pass2(a, 0, MP, gw, NGW, lane); GEMM_N1024(EpiN1024<2>, A_HID, WS_WDN, MS, DFF, MP, G, bx, (bf16_t*)(a.ws + A_GA), nullptr, (float*)(a.ws + WS_RSS2)); }
;     } PHEND
.LBB0_1307:
	s_cmp_lt_i32 s56, 13
	s_cselect_b64 s[6:7], -1, 0
	s_cmp_gt_i32 s57, 12
	s_cselect_b64 s[0:1], -1, 0
	s_and_b64 s[0:1], s[6:7], s[0:1]
	s_andn2_b64 vcc, exec, s[0:1]
	s_cbranch_vccnz .LBB0_1460
	s_andn2_b64 vcc, exec, s[10:11]
	s_cbranch_vccnz .LBB0_1362
	s_getreg_b32 s3, hwreg(HW_REG_XCC_ID, 0, 4)
	s_waitcnt vmcnt(0)
	v_cmp_eq_u32_e32 vcc, 0, v178
	s_waitcnt vmcnt(0) lgkmcnt(0)
	s_barrier
	s_and_saveexec_b64 s[0:1], vcc
	s_cbranch_execz .LBB0_1361
	buffer_inv sc1
	v_mov_b32_e32 v0, 0x23ff0
	ds_read2_b32 v[0:1], v0 offset1:1
	s_and_b32 s98, s3, 15
	s_lshl_b32 s98, s98, 8
	s_add_u32 s98, s54, s98
	s_addc_u32 s99, s55, 0
	s_add_u32 s98, s98, 0x22a3400
	s_addc_u32 s99, s99, 0
	v_mov_b32_e32 v2, 0
	v_mov_b32_e32 v3, 1
	global_atomic_add v4, v2, v3, s[98:99] sc0
	s_add_u32 s100, s54, 0x22a5400
	s_addc_u32 s101, s55, 0
	s_waitcnt vmcnt(0) lgkmcnt(0)
	v_mul_u32_u24_e32 v0, 11, v0
	v_mul_u32_u24_e32 v1, 11, v1
	v_add_u32_e32 v4, 1, v4
	v_cmp_eq_u32_e32 vcc, v4, v0
	s_cbranch_vccz .Lxb_poll_s10
	buffer_wbl2 sc1
	s_waitcnt vmcnt(0)
	global_atomic_add v2, v3, s[100:101]

; __device__ __forceinline__ unsigned xb_ld(unsigned* p)              { return __hip_atomic_load(p, __ATOMIC_RELAXED, __HIP_MEMORY_SCOPE_AGENT); }
; __device__ __forceinline__ unsigned xb_add(unsigned* p, unsigned v) { return __hip_atomic_fetch_add(p, v, __ATOMIC_RELAXED, __HIP_MEMORY_SCOPE_AGENT); }
; #define XB_SPIN(cond, bar) do { unsigned _sp = 0; while (cond) { __builtin_amdgcn_s_sleep(1); \
;     if ((++_sp & 255u) == 0u) { if (xb_ld(&(bar)[XB_TMO])) break; if (_sp > XB_SPIN_CAP) { atomicAdd(&(bar)[XB_TMO], 1u); break; } } } } while (0)
; #define PH(k) if (a.ph_lo <= (k) && (k) < a.ph_hi) { if ((k) > a.ph_lo && (k) != 6) SEAM(k);
; __device__ __forceinline__ void xcd_barrier(const XcdBarrier& b) {
;     asm volatile("s_waitcnt vmcnt(0)" ::: "memory");
;     __syncthreads();
;     if (threadIdx.x == 0) {
;         unsigned* bar = b.bar;
;         __builtin_amdgcn_s_waitcnt(0);
;         unsigned nloc = b.st[0], nx = b.st[1];
;         if (nloc == 0u) { xcd_barrier_complete(bar, b.x, nloc, nx); b.st[0] = nloc; b.st[1] = nx; }
;         const unsigned old = xb_add(&bar[XB_XSUB(b.x)], 1u);
;         const unsigned gen = old / nloc;
;         if (old + 1u == (gen + 1u) * nloc) {
;             __builtin_amdgcn_fence(__ATOMIC_RELEASE, "agent");
;             asm volatile("s_waitcnt vmcnt(0)" ::: "memory");
;             const unsigned og = xb_add(&bar[XB_TOP], 1u);
;             const unsigned tg = og / nx;
;             if (og + 1u == (tg + 1u) * nx) xb_add(&bar[XB_TOPGEN], 1u);
;             else XB_SPIN(xb_ld(&bar[XB_TOPGEN]) == tg, bar);
;             __builtin_amdgcn_fence(__ATOMIC_ACQUIRE, "agent");
;             xb_add(&bar[XB_XGEN(b.x)], 1u);
;             asm volatile("s_waitcnt vmcnt(0)" ::: "memory");
;         } else {
;             XB_SPIN(xb_ld(&bar[XB_XGEN(b.x)]) == gen, bar);
;             __builtin_amdgcn_fence(__ATOMIC_ACQUIRE, "agent");
;             asm volatile("s_waitcnt vmcnt(0)" ::: "memory");
;         }
;     }
;     __syncthreads();
; }
; __global__ void __launch_bounds__(512) fwd_kernel(Args a) {
;     ...
;     PH(13) { row_pass2(a, MP, MT, gw, NGW, lane); } PHEND
.LBB0_1460:
	s_cmp_lt_i32 s56, 14
	s_cselect_b64 s[0:1], -1, 0
	s_cmp_gt_i32 s57, 13
	s_cselect_b64 s[4:5], -1, 0
	s_and_b64 s[0:1], s[0:1], s[4:5]
	s_andn2_b64 vcc, exec, s[0:1]
	s_cbranch_vccnz .LBB0_1520
	s_andn2_b64 vcc, exec, s[6:7]
	s_cbranch_vccnz .LBB0_1515
	s_getreg_b32 s3, hwreg(HW_REG_XCC_ID, 0, 4)
	s_waitcnt vmcnt(0)
	v_cmp_eq_u32_e32 vcc, 0, v178
	s_waitcnt vmcnt(0) lgkmcnt(0)
	s_barrier
	s_and_saveexec_b64 s[0:1], vcc
	s_cbranch_execz .LBB0_1514
	buffer_inv sc1
	v_mov_b32_e32 v0, 0x23ff0
	ds_read2_b32 v[0:1], v0 offset1:1
	s_and_b32 s98, s3, 15
	s_lshl_b32 s98, s98, 8
	s_add_u32 s98, s54, s98
	s_addc_u32 s99, s55, 0
	s_add_u32 s98, s98, 0x22a3400
	s_addc_u32 s99, s99, 0
	v_mov_b32_e32 v2, 0
	v_mov_b32_e32 v3, 1
	global_atomic_add v4, v2, v3, s[98:99] sc0
	s_add_u32 s100, s54, 0x22a5400
	s_addc_u32 s101, s55, 0
	s_waitcnt vmcnt(0) lgkmcnt(0)
	v_mul_u32_u24_e32 v0, 12, v0
	v_mul_u32_u24_e32 v1, 12, v1
	v_add_u32_e32 v4, 1, v4
	v_cmp_eq_u32_e32 vcc, v4, v0
	s_cbranch_vccz .Lxb_poll_s11
	buffer_wbl2 sc1
	s_waitcnt vmcnt(0)
	global_atomic_add v2, v3, s[100:101]
